# scan with direct-from-global W / QD fragments, counted waits that leave the next chunk's loads in flight
# speedup vs baseline: 1.0068x; 1.0068x over previous
.Lscan_loop:
	s_and_b32 s7, s6, 3
	s_lshl_b32 s7, s7, 12
	v_add_u32_e32 v23, s7, v22
	ds_read_b128 v[32:35], v10 offset:0
	ds_read_b128 v[36:39], v10 offset:64
	ds_read_b128 v[40:43], v10 offset:128
	ds_read_b128 v[44:47], v10 offset:192
	ds_read_u16 v80, v23 offset:0
	ds_read_u16 v81, v23 offset:64
	ds_read_u16 v82, v23 offset:128
	ds_read_u16 v83, v23 offset:192
	s_add_u32 s33, s6, 1
	s_min_u32 s33, s33, 31
	s_add_u32 s36, s6, 2
	s_min_u32 s36, s36, 31
	s_lshl_b32 s7, s33, 14
	s_add_u32 s26, s10, s7
	s_addc_u32 s27, s11, 0
	global_load_dwordx4 v[162:165], v136, s[26:27] offset:0
	global_load_dwordx4 v[166:169], v136, s[26:27] offset:64
	global_load_dwordx4 v[170:173], v136, s[26:27] offset:128
	global_load_dwordx4 v[174:177], v136, s[26:27] offset:192
	s_lshl_b32 s7, s33, 14
	s_add_u32 s28, s12, s7
	s_addc_u32 s29, s13, 0
	global_load_dwordx4 v[178:181], v136, s[28:29] offset:0
	global_load_dwordx4 v[182:185], v136, s[28:29] offset:64
	global_load_dwordx4 v[186:189], v136, s[28:29] offset:128
	global_load_dwordx4 v[190:193], v136, s[28:29] offset:192
	v_readlane_b32 s37, v24, s6
	s_nop 1
	v_mul_f32_e32 v92, s37, v92
	v_mul_f32_e32 v93, s37, v93
	v_mul_f32_e32 v94, s37, v94
	v_mul_f32_e32 v95, s37, v95
	v_mul_f32_e32 v96, s37, v96
	v_mul_f32_e32 v97, s37, v97
	v_mul_f32_e32 v98, s37, v98
	v_mul_f32_e32 v99, s37, v99
	s_waitcnt vmcnt(13)
	s_waitcnt lgkmcnt(7)
	v_mfma_f32_16x16x32_bf16 v[84:87], v[48:51], v[32:35], 0
	s_waitcnt lgkmcnt(6)
	v_mfma_f32_16x16x32_bf16 v[84:87], v[52:55], v[36:39], v[84:87]
	s_waitcnt lgkmcnt(5)
	v_mfma_f32_16x16x32_bf16 v[84:87], v[56:59], v[40:43], v[84:87]
	s_waitcnt lgkmcnt(4)
	v_mfma_f32_16x16x32_bf16 v[84:87], v[60:63], v[44:47], v[84:87]
	s_waitcnt lgkmcnt(0)
	s_nop 4
	v_lshlrev_b32_e32 v80, 16, v80
	v_lshlrev_b32_e32 v81, 16, v81
	v_lshlrev_b32_e32 v82, 16, v82
	v_lshlrev_b32_e32 v83, 16, v83
	v_sub_f32_e32 v26, v80, v84
	v_sub_f32_e32 v27, v81, v85
	v_sub_f32_e32 v28, v82, v86
	v_sub_f32_e32 v29, v83, v87
	v_cvt_pk_bf16_f32 v26, v26, v27
	v_cvt_pk_bf16_f32 v27, v28, v29
	ds_write_b64 v20, v[26:27]
	s_lshl_b32 s7, s33, 14
	s_add_u32 s26, s14, s7
	s_addc_u32 s27, s15, 0
	s_add_i32 m0, s30, 0x14000
	s_nop 0
	global_load_lds_dwordx4 v5, s[26:27]
	s_add_i32 m0, s30, 0x14400
	s_nop 0
	global_load_lds_dwordx4 v6, s[26:27]
	s_lshl_b32 s7, s33, 13
	s_add_u32 s28, s18, s7
	s_addc_u32 s29, s19, 0
	s_add_i32 m0, s31, 0x1a000
	s_nop 0
	global_load_lds_dwordx4 v7, s[28:29]
	s_lshl_b32 s7, s36, 14
	s_add_u32 s26, s24, s7
	s_addc_u32 s27, s25, 0
	s_add_u32 s8, s6, 2
	s_and_b32 s8, s8, 3
	s_lshl_b32 s8, s8, 12
	s_add_u32 s8, s8, s32
	s_add_i32 m0, s8, 0x1f400
	s_nop 0
	global_load_lds_dwordx4 v8, s[26:27]
	s_waitcnt vmcnt(13) lgkmcnt(0)
	s_barrier
	ds_read_b128 v[100:103], v19
	ds_read_b128 v[108:111], v15 offset:0
	ds_read_b128 v[112:115], v15 offset:2048
	ds_read_b128 v[104:107], v19 offset:64
	ds_read_b128 v[116:119], v16 offset:0
	ds_read_b128 v[120:123], v16 offset:2048
	ds_read_b128 v[124:127], v17 offset:0
	ds_read_b128 v[128:131], v18 offset:0
	v_mfma_f32_16x16x32_bf16 v[88:91], v[32:35], v[64:67], 0
	v_mfma_f32_16x16x32_bf16 v[88:91], v[36:39], v[68:71], v[88:91]
	v_mfma_f32_16x16x32_bf16 v[88:91], v[40:43], v[72:75], v[88:91]
	v_mfma_f32_16x16x32_bf16 v[88:91], v[44:47], v[76:79], v[88:91]
	s_waitcnt lgkmcnt(6)
	v_mfma_f32_16x16x32_bf16 v[92:95], v[108:111], v[100:103], v[92:95]
	s_waitcnt lgkmcnt(5)
	v_mfma_f32_16x16x32_bf16 v[96:99], v[112:115], v[100:103], v[96:99]
	s_waitcnt lgkmcnt(3)
	v_mfma_f32_16x16x32_bf16 v[92:95], v[116:119], v[104:107], v[92:95]
	s_waitcnt lgkmcnt(2)
	v_mfma_f32_16x16x32_bf16 v[96:99], v[120:123], v[104:107], v[96:99]
	s_waitcnt lgkmcnt(1)
	v_mfma_f32_16x16x32_bf16 v[88:91], v[100:103], v[124:127], v[88:91]
	s_waitcnt lgkmcnt(0)
	v_mfma_f32_16x16x32_bf16 v[88:91], v[104:107], v[128:131], v[88:91]
	s_lshl_b32 s7, s6, 14
	s_add_u32 s28, s24, s7
	s_addc_u32 s29, s25, 0
	s_nop 1
	v_cvt_pk_bf16_f32 v26, v92, v93
	v_cvt_pk_bf16_f32 v27, v94, v95
	v_cvt_pk_bf16_f32 v28, v96, v97
	v_cvt_pk_bf16_f32 v29, v98, v99
	ds_write_b64 v21, v[26:27]
	ds_write_b64 v21, v[28:29] offset:32
	v_cvt_pk_bf16_f32 v80, v88, v89
	v_cvt_pk_bf16_f32 v81, v90, v91
	global_store_dwordx2 v9, v[80:81], s[28:29]
	s_add_u32 s6, s6, 1
	s_waitcnt vmcnt(13) lgkmcnt(0)
	s_barrier
	s_and_b32 s7, s6, 3
	s_lshl_b32 s7, s7, 12
	v_add_u32_e32 v23, s7, v22
	ds_read_b128 v[32:35], v10 offset:0
	ds_read_b128 v[36:39], v10 offset:64
	ds_read_b128 v[40:43], v10 offset:128
	ds_read_b128 v[44:47], v10 offset:192
	ds_read_u16 v80, v23 offset:0
	ds_read_u16 v81, v23 offset:64
	ds_read_u16 v82, v23 offset:128
	ds_read_u16 v83, v23 offset:192
	s_add_u32 s33, s6, 1
	s_min_u32 s33, s33, 31
	s_add_u32 s36, s6, 2
	s_min_u32 s36, s36, 31
	s_lshl_b32 s7, s33, 14
	s_add_u32 s26, s10, s7
	s_addc_u32 s27, s11, 0
	global_load_dwordx4 v[48:51], v136, s[26:27] offset:0
	global_load_dwordx4 v[52:55], v136, s[26:27] offset:64
	global_load_dwordx4 v[56:59], v136, s[26:27] offset:128
	global_load_dwordx4 v[60:63], v136, s[26:27] offset:192
	s_lshl_b32 s7, s33, 14
	s_add_u32 s28, s12, s7
	s_addc_u32 s29, s13, 0
	global_load_dwordx4 v[64:67], v136, s[28:29] offset:0
	global_load_dwordx4 v[68:71], v136, s[28:29] offset:64
	global_load_dwordx4 v[72:75], v136, s[28:29] offset:128
	global_load_dwordx4 v[76:79], v136, s[28:29] offset:192
	v_readlane_b32 s37, v24, s6
	s_nop 1
	v_mul_f32_e32 v92, s37, v92
	v_mul_f32_e32 v93, s37, v93
	v_mul_f32_e32 v94, s37, v94
	v_mul_f32_e32 v95, s37, v95
	v_mul_f32_e32 v96, s37, v96
	v_mul_f32_e32 v97, s37, v97
	v_mul_f32_e32 v98, s37, v98
	v_mul_f32_e32 v99, s37, v99
	s_waitcnt vmcnt(13)
	s_waitcnt lgkmcnt(7)
	v_mfma_f32_16x16x32_bf16 v[84:87], v[162:165], v[32:35], 0
	s_waitcnt lgkmcnt(6)
	v_mfma_f32_16x16x32_bf16 v[84:87], v[166:169], v[36:39], v[84:87]
	s_waitcnt lgkmcnt(5)
	v_mfma_f32_16x16x32_bf16 v[84:87], v[170:173], v[40:43], v[84:87]
	s_waitcnt lgkmcnt(4)
	v_mfma_f32_16x16x32_bf16 v[84:87], v[174:177], v[44:47], v[84:87]
	s_waitcnt lgkmcnt(0)
	s_nop 4
	v_lshlrev_b32_e32 v80, 16, v80
	v_lshlrev_b32_e32 v81, 16, v81
	v_lshlrev_b32_e32 v82, 16, v82
	v_lshlrev_b32_e32 v83, 16, v83
	v_sub_f32_e32 v26, v80, v84
	v_sub_f32_e32 v27, v81, v85
	v_sub_f32_e32 v28, v82, v86
	v_sub_f32_e32 v29, v83, v87
	v_cvt_pk_bf16_f32 v26, v26, v27
	v_cvt_pk_bf16_f32 v27, v28, v29
	ds_write_b64 v20, v[26:27]
	s_lshl_b32 s7, s33, 14
	s_add_u32 s26, s14, s7
	s_addc_u32 s27, s15, 0
	s_add_i32 m0, s30, 0x10000
	s_nop 0
	global_load_lds_dwordx4 v5, s[26:27]
	s_add_i32 m0, s30, 0x10400
	s_nop 0
	global_load_lds_dwordx4 v6, s[26:27]
	s_lshl_b32 s7, s33, 13
	s_add_u32 s28, s18, s7
	s_addc_u32 s29, s19, 0
	s_add_i32 m0, s31, 0x18000
	s_nop 0
	global_load_lds_dwordx4 v7, s[28:29]
	s_lshl_b32 s7, s36, 14
	s_add_u32 s26, s24, s7
	s_addc_u32 s27, s25, 0
	s_add_u32 s8, s6, 2
	s_and_b32 s8, s8, 3
	s_lshl_b32 s8, s8, 12
	s_add_u32 s8, s8, s32
	s_add_i32 m0, s8, 0x1f400
	s_nop 0
	global_load_lds_dwordx4 v8, s[26:27]
	s_waitcnt vmcnt(13) lgkmcnt(0)
	s_barrier
	ds_read_b128 v[100:103], v19
	ds_read_b128 v[108:111], v15 offset:16384
	ds_read_b128 v[112:115], v15 offset:18432
	ds_read_b128 v[104:107], v19 offset:64
	ds_read_b128 v[116:119], v16 offset:16384
	ds_read_b128 v[120:123], v16 offset:18432
	ds_read_b128 v[124:127], v17 offset:8192
	ds_read_b128 v[128:131], v18 offset:8192
	v_mfma_f32_16x16x32_bf16 v[88:91], v[32:35], v[178:181], 0
	v_mfma_f32_16x16x32_bf16 v[88:91], v[36:39], v[182:185], v[88:91]
	v_mfma_f32_16x16x32_bf16 v[88:91], v[40:43], v[186:189], v[88:91]
	v_mfma_f32_16x16x32_bf16 v[88:91], v[44:47], v[190:193], v[88:91]
	s_waitcnt lgkmcnt(6)
	v_mfma_f32_16x16x32_bf16 v[92:95], v[108:111], v[100:103], v[92:95]
	s_waitcnt lgkmcnt(5)
	v_mfma_f32_16x16x32_bf16 v[96:99], v[112:115], v[100:103], v[96:99]
	s_waitcnt lgkmcnt(3)
	v_mfma_f32_16x16x32_bf16 v[92:95], v[116:119], v[104:107], v[92:95]
	s_waitcnt lgkmcnt(2)
	v_mfma_f32_16x16x32_bf16 v[96:99], v[120:123], v[104:107], v[96:99]
	s_waitcnt lgkmcnt(1)
	v_mfma_f32_16x16x32_bf16 v[88:91], v[100:103], v[124:127], v[88:91]
	s_waitcnt lgkmcnt(0)
	v_mfma_f32_16x16x32_bf16 v[88:91], v[104:107], v[128:131], v[88:91]
	s_lshl_b32 s7, s6, 14
	s_add_u32 s28, s24, s7
	s_addc_u32 s29, s25, 0
	s_nop 1
	v_cvt_pk_bf16_f32 v26, v92, v93
	v_cvt_pk_bf16_f32 v27, v94, v95
	v_cvt_pk_bf16_f32 v28, v96, v97
	v_cvt_pk_bf16_f32 v29, v98, v99
	ds_write_b64 v21, v[26:27]
	ds_write_b64 v21, v[28:29] offset:32
	v_cvt_pk_bf16_f32 v80, v88, v89
	v_cvt_pk_bf16_f32 v81, v90, v91
	global_store_dwordx2 v9, v[80:81], s[28:29]
	s_add_u32 s6, s6, 1
	s_waitcnt vmcnt(13) lgkmcnt(0)
	s_barrier
	s_cmp_lt_u32 s6, 32
	s_cbranch_scc1 .Lscan_loop
	s_lshl_b32 s56, s77, 5
	s_and_b32 s57, s40, 3
	s_lshl_b32 s72, s40, 5
	s_waitcnt vmcnt(0)
	v_readfirstlane_b32 s3, v194
	s_cmp_gt_u32 s3, 63
	s_barrier
	s_cbranch_scc1 .LBB0_421
	s_waitcnt vmcnt(2)
	v_mbcnt_lo_u32_b32 v0, -1, 0
	v_mbcnt_hi_u32_b32 v0, -1, v0
	s_nop 0
	v_cmp_eq_u32_e32 vcc, 0, v0
	s_and_saveexec_b64 s[6:7], vcc
	s_cbranch_execz .LBB0_420
	s_add_i32 s3, 0, 0x23ff0
	v_mov_b32_e32 v0, s3
	s_waitcnt vmcnt(0) expcnt(0) lgkmcnt(0)
	ds_read_b32 v2, v0
	s_add_i32 s3, 0, 0x23ff4
	v_mov_b32_e32 v0, s3
	ds_read_b32 v0, v0
	s_waitcnt lgkmcnt(1)
	v_cmp_ne_u32_e32 vcc, 0, v2
	s_cbranch_vccnz .LBB0_384
	s_mov_b32 s3, 1
	v_mov_b32_e32 v16, 0
	s_branch .LBB0_372
